# P2: half the workgroups run the sample-path item after the attention/local-state items (spreads the HBM-bound KV gather in time)
# speedup vs baseline: 1.0327x; 1.0095x over previous
.LBB0_289:
	s_or_b64 exec, exec, s[0:1]
	s_add_u32 s0, s24, 0x10000000
	s_addc_u32 s1, s25, 0
	v_writelane_b32 v247, s0, 21
	v_mov_b32_e32 v209, v222
	s_waitcnt lgkmcnt(0)
	v_writelane_b32 v247, s1, 22
	s_barrier
	v_writelane_b32 v247, s92, 23
	s_cmpk_lt_i32 s92, 0x100
	s_nop 0
	v_bfe_u32 v193, v209, 4, 2
	v_ashrrev_i32_e32 v112, 3, v209
	v_and_b32_e32 v189, 15, v209
	v_writelane_b32 v247, s93, 24
	s_mov_b32 s100, 0
	s_cbranch_scc0 .LBB0_394
	s_bitcmp1_b32 s92, 3
	s_cbranch_scc0 .Lstag_sample
	s_mov_b32 s100, 1
	s_branch .LBB0_394
.Lstag_sample:
	v_cmp_gt_i32_e64 s[0:1], 64, v209
	v_ashrrev_i32_e32 v101, 6, v209
	v_and_b32_e32 v0, 7, v209
	v_writelane_b32 v247, s0, 26
	v_and_b32_e32 v100, 63, v209
	v_lshlrev_b32_e32 v2, 3, v101
	v_writelane_b32 v247, s1, 27
	v_cmp_ge_i32_e64 s[0:1], v112, v0
	v_mov_b32_e32 v105, 0
	v_ashrrev_i32_e32 v3, 31, v2
	v_writelane_b32 v247, s0, 28
	v_lshlrev_b32_e32 v104, 2, v100
	v_lshlrev_b64 v[106:107], 6, v[2:3]
	v_writelane_b32 v247, s1, 29
	v_lshl_add_u64 v[2:3], s[22:23], 0, v[104:105]
	s_mov_b64 s[0:1], 0x4180000
	v_lshl_add_u64 v[110:111], v[2:3], 0, s[0:1]
	v_mbcnt_hi_u32_b32 v3, -1, v223
	v_and_b32_e32 v5, 64, v3
	v_add_u32_e32 v5, 64, v5
	v_xor_b32_e32 v6, 1, v3
	v_cmp_lt_i32_e32 vcc, v6, v5
	v_cmp_lt_i32_e64 s[0:1], -1, v101
	v_lshl_add_u32 v115, v112, 8, 0
	v_cndmask_b32_e32 v6, v3, v6, vcc
	v_lshlrev_b32_e32 v213, 2, v6
	v_xor_b32_e32 v6, 2, v3
	v_cmp_lt_i32_e32 vcc, v6, v5
	v_writelane_b32 v247, s0, 30
	v_lshl_add_u32 v114, v101, 5, 0
	v_cndmask_b32_e32 v6, v3, v6, vcc
	v_lshlrev_b32_e32 v214, 2, v6
	v_xor_b32_e32 v6, 4, v3
	v_cmp_lt_i32_e32 vcc, v6, v5
	v_and_b32_e32 v2, 0x3fffffc0, v209
	v_writelane_b32 v247, s1, 31
	v_cndmask_b32_e32 v6, v3, v6, vcc
	v_lshlrev_b32_e32 v215, 2, v6
	v_xor_b32_e32 v6, 8, v3
	v_cmp_lt_i32_e32 vcc, v6, v5
	s_movk_i32 s0, 0x6e0
	v_lshl_add_u32 v2, v2, 2, 0
	v_cndmask_b32_e32 v6, v3, v6, vcc
	v_lshlrev_b32_e32 v216, 2, v6
	v_xor_b32_e32 v6, 16, v3
	v_cmp_lt_i32_e32 vcc, v6, v5
	v_mad_u64_u32 v[118:119], s[0:1], v101, s0, v[114:115]
	s_nop 0
	v_cndmask_b32_e32 v6, v3, v6, vcc
	v_lshlrev_b32_e32 v217, 2, v6
	v_xor_b32_e32 v6, 32, v3
	v_cmp_lt_i32_e32 vcc, v6, v5
	v_add_u32_e32 v219, 0x800, v101
	v_add_u32_e32 v211, v2, v104
	v_cndmask_b32_e32 v3, v3, v6, vcc
	v_lshl_add_u32 v119, v189, 4, v2
	s_movk_i32 s33, 0x800
	v_sub_u32_e32 v2, v219, v193
	v_lshlrev_b32_e32 v218, 2, v3
	v_cmp_gt_i32_e64 s[0:1], s33, v2
	v_add_u32_e32 v28, 0xfffff800, v2
	v_ashrrev_i32_e32 v3, 31, v2
	v_or_b32_e32 v5, 4, v193
	v_cndmask_b32_e64 v3, 0, v3, s[0:1]
	v_writelane_b32 v247, s0, 32
	v_or_b32_e32 v6, 8, v193
	v_or_b32_e32 v7, 12, v193
	v_cndmask_b32_e64 v2, v28, v2, s[0:1]
	v_lshlrev_b64 v[120:121], 11, v[2:3]
	v_sub_u32_e32 v2, v219, v5
	v_writelane_b32 v247, s1, 33
	v_cmp_gt_i32_e64 s[0:1], s33, v2
	v_ashrrev_i32_e32 v3, 31, v2
	v_add_u32_e32 v5, 0xfffff800, v2
	v_cndmask_b32_e64 v3, 0, v3, s[0:1]
	v_writelane_b32 v247, s0, 34
	v_or_b32_e32 v8, 16, v193
	v_or_b32_e32 v9, 20, v193
	v_cndmask_b32_e64 v2, v5, v2, s[0:1]
	v_lshlrev_b64 v[122:123], 11, v[2:3]
	v_sub_u32_e32 v2, v219, v6
	v_writelane_b32 v247, s1, 35
	v_cmp_gt_i32_e64 s[0:1], s33, v2
	v_ashrrev_i32_e32 v3, 31, v2
	v_add_u32_e32 v5, 0xfffff800, v2
	v_cndmask_b32_e64 v3, 0, v3, s[0:1]
	v_writelane_b32 v247, s0, 36
	v_or_b32_e32 v10, 24, v193
	v_or_b32_e32 v11, 28, v193
	v_cndmask_b32_e64 v2, v5, v2, s[0:1]
	v_lshlrev_b64 v[124:125], 11, v[2:3]
	v_sub_u32_e32 v2, v219, v7
	v_writelane_b32 v247, s1, 37
	v_cmp_gt_i32_e64 s[0:1], s33, v2
	v_ashrrev_i32_e32 v3, 31, v2
	v_add_u32_e32 v5, 0xfffff800, v2
	v_cndmask_b32_e64 v3, 0, v3, s[0:1]
	v_writelane_b32 v247, s0, 38
	v_or_b32_e32 v12, 32, v193
	v_or_b32_e32 v13, 36, v193
	v_cndmask_b32_e64 v2, v5, v2, s[0:1]
	v_lshlrev_b64 v[126:127], 11, v[2:3]
	v_sub_u32_e32 v2, v219, v8
	v_writelane_b32 v247, s1, 39
	v_cmp_gt_i32_e64 s[0:1], s33, v2
	v_ashrrev_i32_e32 v3, 31, v2
	v_add_u32_e32 v5, 0xfffff800, v2
	v_cndmask_b32_e64 v3, 0, v3, s[0:1]
	v_writelane_b32 v247, s0, 40
	v_or_b32_e32 v14, 40, v193
	v_or_b32_e32 v15, 44, v193
	v_cndmask_b32_e64 v2, v5, v2, s[0:1]
	v_lshlrev_b64 v[128:129], 11, v[2:3]
	v_sub_u32_e32 v2, v219, v9
	v_cmp_gt_i32_e64 s[94:95], s33, v2
	v_ashrrev_i32_e32 v3, 31, v2
	v_add_u32_e32 v5, 0xfffff800, v2
	v_cndmask_b32_e64 v3, 0, v3, s[94:95]
	v_cndmask_b32_e64 v2, v5, v2, s[94:95]
	v_lshlrev_b64 v[130:131], 11, v[2:3]
	v_sub_u32_e32 v2, v219, v10
	v_cmp_gt_i32_e64 s[96:97], s33, v2
	v_ashrrev_i32_e32 v3, 31, v2
	v_add_u32_e32 v5, 0xfffff800, v2
	v_cndmask_b32_e64 v3, 0, v3, s[96:97]
	v_cndmask_b32_e64 v2, v5, v2, s[96:97]
	v_lshlrev_b64 v[132:133], 11, v[2:3]
	v_sub_u32_e32 v2, v219, v11
	v_cmp_gt_i32_e64 s[72:73], s33, v2
	v_ashrrev_i32_e32 v3, 31, v2
	v_add_u32_e32 v5, 0xfffff800, v2
	v_cndmask_b32_e64 v3, 0, v3, s[72:73]
	v_cndmask_b32_e64 v2, v5, v2, s[72:73]
	v_lshlrev_b64 v[134:135], 11, v[2:3]
	v_sub_u32_e32 v2, v219, v12
	v_cmp_gt_i32_e64 s[28:29], s33, v2
	v_ashrrev_i32_e32 v3, 31, v2
	v_add_u32_e32 v5, 0xfffff800, v2
	v_cndmask_b32_e64 v3, 0, v3, s[28:29]
	v_cndmask_b32_e64 v2, v5, v2, s[28:29]
	v_lshlrev_b64 v[136:137], 11, v[2:3]
	v_sub_u32_e32 v2, v219, v13
	v_cmp_gt_i32_e64 s[30:31], s33, v2
	v_ashrrev_i32_e32 v3, 31, v2
	v_add_u32_e32 v5, 0xfffff800, v2
	v_cndmask_b32_e64 v3, 0, v3, s[30:31]
	v_cndmask_b32_e64 v2, v5, v2, s[30:31]
	v_lshlrev_b64 v[138:139], 11, v[2:3]
	v_sub_u32_e32 v2, v219, v14
	v_cmp_gt_i32_e64 s[34:35], s33, v2
	v_ashrrev_i32_e32 v3, 31, v2
	v_add_u32_e32 v5, 0xfffff800, v2
	v_cndmask_b32_e64 v3, 0, v3, s[34:35]
	v_cndmask_b32_e64 v2, v5, v2, s[34:35]
	v_lshlrev_b64 v[140:141], 11, v[2:3]
	v_sub_u32_e32 v2, v219, v15
	v_cmp_gt_i32_e64 s[40:41], s33, v2
	v_ashrrev_i32_e32 v3, 31, v2
	v_add_u32_e32 v5, 0xfffff800, v2
	v_or_b32_e32 v16, 48, v193
	v_cndmask_b32_e64 v3, 0, v3, s[40:41]
	v_cndmask_b32_e64 v2, v5, v2, s[40:41]
	v_lshlrev_b64 v[142:143], 11, v[2:3]
	v_sub_u32_e32 v2, v219, v16
	v_cmp_gt_i32_e64 s[42:43], s33, v2
	v_ashrrev_i32_e32 v3, 31, v2
	v_add_u32_e32 v5, 0xfffff800, v2
	v_or_b32_e32 v17, 52, v193
	v_cndmask_b32_e64 v3, 0, v3, s[42:43]
	v_cndmask_b32_e64 v2, v5, v2, s[42:43]
	v_lshlrev_b64 v[144:145], 11, v[2:3]
	v_sub_u32_e32 v2, v219, v17
	v_cmp_gt_i32_e64 s[44:45], s33, v2
	v_ashrrev_i32_e32 v3, 31, v2
	v_add_u32_e32 v5, 0xfffff800, v2
	v_or_b32_e32 v18, 56, v193
	v_cndmask_b32_e64 v3, 0, v3, s[44:45]
	v_cndmask_b32_e64 v2, v5, v2, s[44:45]
	v_lshlrev_b64 v[146:147], 11, v[2:3]
	v_sub_u32_e32 v2, v219, v18
	v_cmp_gt_i32_e64 s[50:51], s33, v2
	v_ashrrev_i32_e32 v3, 31, v2
	v_add_u32_e32 v5, 0xfffff800, v2
	v_or_b32_e32 v19, 60, v193
	v_cndmask_b32_e64 v3, 0, v3, s[50:51]
	v_cndmask_b32_e64 v2, v5, v2, s[50:51]
	v_lshlrev_b64 v[148:149], 11, v[2:3]
	v_sub_u32_e32 v2, v219, v19
	v_cmp_gt_i32_e64 s[74:75], s33, v2
	v_ashrrev_i32_e32 v3, 31, v2
	v_add_u32_e32 v5, 0xfffff800, v2
	v_or_b32_e32 v20, 64, v193
	v_cndmask_b32_e64 v3, 0, v3, s[74:75]
	v_cndmask_b32_e64 v2, v5, v2, s[74:75]
	v_lshlrev_b64 v[150:151], 11, v[2:3]
	v_sub_u32_e32 v2, v219, v20
	v_lshl_add_u64 v[108:109], s[80:81], 0, v[104:105]
	v_cmp_gt_i32_e64 s[80:81], s33, v2
	v_ashrrev_i32_e32 v3, 31, v2
	v_add_u32_e32 v5, 0xfffff800, v2
	v_or_b32_e32 v21, 0x44, v193
	v_cndmask_b32_e64 v3, 0, v3, s[80:81]
	v_cndmask_b32_e64 v2, v5, v2, s[80:81]
	v_lshlrev_b64 v[152:153], 11, v[2:3]
	v_sub_u32_e32 v2, v219, v21
	v_cmp_gt_i32_e64 s[88:89], s33, v2
	v_ashrrev_i32_e32 v3, 31, v2
	v_add_u32_e32 v5, 0xfffff800, v2
	v_or_b32_e32 v22, 0x48, v193
	v_cndmask_b32_e64 v3, 0, v3, s[88:89]
	v_cndmask_b32_e64 v2, v5, v2, s[88:89]
	v_lshlrev_b64 v[154:155], 11, v[2:3]
	v_sub_u32_e32 v2, v219, v22
	v_cmp_gt_i32_e64 s[90:91], s33, v2
	v_ashrrev_i32_e32 v3, 31, v2
	v_add_u32_e32 v5, 0xfffff800, v2
	v_or_b32_e32 v23, 0x4c, v193
	v_cndmask_b32_e64 v3, 0, v3, s[90:91]
	v_cndmask_b32_e64 v2, v5, v2, s[90:91]
	v_lshlrev_b64 v[156:157], 11, v[2:3]
	v_sub_u32_e32 v2, v219, v23
	v_cmp_gt_i32_e64 s[52:53], s33, v2
	v_ashrrev_i32_e32 v3, 31, v2
	v_add_u32_e32 v5, 0xfffff800, v2
	v_or_b32_e32 v24, 0x50, v193
	v_cndmask_b32_e64 v3, 0, v3, s[52:53]
	v_cndmask_b32_e64 v2, v5, v2, s[52:53]
	v_lshlrev_b64 v[158:159], 11, v[2:3]
	v_sub_u32_e32 v2, v219, v24
	v_cmp_gt_i32_e64 s[54:55], s33, v2
	v_ashrrev_i32_e32 v3, 31, v2
	v_add_u32_e32 v5, 0xfffff800, v2
	v_or_b32_e32 v220, 0x54, v193
	v_cndmask_b32_e64 v3, 0, v3, s[54:55]
	v_cndmask_b32_e64 v2, v5, v2, s[54:55]
	v_lshlrev_b64 v[160:161], 11, v[2:3]
	v_sub_u32_e32 v2, v219, v220
	v_cmp_gt_i32_e64 s[56:57], s33, v2
	v_ashrrev_i32_e32 v3, 31, v2
	v_add_u32_e32 v5, 0xfffff800, v2
	v_or_b32_e32 v25, 0x58, v193
	v_cndmask_b32_e64 v3, 0, v3, s[56:57]
	v_cndmask_b32_e64 v2, v5, v2, s[56:57]
	v_writelane_b32 v247, s1, 41
	v_lshlrev_b64 v[162:163], 11, v[2:3]
	v_sub_u32_e32 v2, v219, v25
	v_cmp_gt_u32_e64 s[0:1], 16, v100
	v_cmp_gt_i32_e64 s[58:59], s33, v2
	v_ashrrev_i32_e32 v3, 31, v2
	v_add_u32_e32 v5, 0xfffff800, v2
	v_writelane_b32 v247, s0, 42
	v_add_u32_e32 v4, 1, v101
	v_or_b32_e32 v26, 0x5c, v193
	v_cndmask_b32_e64 v3, 0, v3, s[58:59]
	v_cndmask_b32_e64 v2, v5, v2, s[58:59]
	v_writelane_b32 v247, s1, 43
	v_cmp_lt_u32_e64 s[0:1], 6, v101
	v_lshlrev_b64 v[164:165], 11, v[2:3]
	v_sub_u32_e32 v2, v219, v26
	v_and_b32_e32 v224, 7, v4
	v_writelane_b32 v247, s0, 44
	v_cmp_gt_i32_e64 s[60:61], s33, v2
	v_ashrrev_i32_e32 v3, 31, v2
	v_add_u32_e32 v5, 0xfffff800, v2
	v_writelane_b32 v247, s1, 45
	v_cmp_ne_u32_e64 s[0:1], 0, v224
	v_or_b32_e32 v27, 0x60, v193
	v_cndmask_b32_e64 v3, 0, v3, s[60:61]
	v_cndmask_b32_e64 v2, v5, v2, s[60:61]
	v_writelane_b32 v247, s0, 46
	v_sub_u32_e32 v1, v112, v0
	v_lshlrev_b64 v[166:167], 11, v[2:3]
	v_sub_u32_e32 v2, v219, v27
	v_writelane_b32 v247, s1, 47
	v_lshl_add_u32 v0, v0, 8, 0
	s_movk_i32 s0, 0x700
	v_cvt_f32_i32_e32 v117, v1
	v_cvt_f32_i32_e32 v212, v4
	v_cmp_gt_i32_e64 s[62:63], s33, v2
	v_ashrrev_i32_e32 v3, 31, v2
	v_add_u32_e32 v5, 0xfffff800, v2
	v_add_u32_e32 v229, 0x800, v0
	v_mul_lo_u32 v0, v101, s0
	v_cndmask_b32_e64 v3, 0, v3, s[62:63]
	v_cndmask_b32_e64 v2, v5, v2, s[62:63]
	v_lshl_or_b32 v0, v193, 2, v0
	v_add_u32_e32 v102, 0x4000, v101
	v_add_u32_e32 v210, 0, v104
	v_lshlrev_b32_e32 v1, 11, v101
	v_lshlrev_b32_e32 v116, 2, v189
	v_lshlrev_b64 v[168:169], 11, v[2:3]
	v_or_b32_e32 v2, 0x180, v100
	s_movk_i32 s14, 0x183
	v_add_u32_e32 v0, 0, v0
	s_mov_b32 s5, 0
	v_lshl_add_u32 v113, v209, 2, 0
	v_ashrrev_i32_e32 v103, 31, v102
	v_cmp_eq_u32_e64 s[10:11], 0, v189
	v_add_u32_e32 v221, v118, v104
	v_cmp_gt_u32_e64 s[64:65], s14, v2
	v_and_b32_e32 v225, 0x7ffffff8, v4
	v_sub_u32_e32 v226, 0x183, v25
	v_sub_u32_e32 v227, 0x183, v26
	v_sub_u32_e32 v228, 0x183, v27
	v_add_u32_e32 v230, 0x2000, v114
	v_add_u32_e32 v231, 0x1000, v210
	v_add_u32_e32 v232, 0x6100, v0
	s_movk_i32 s15, 0x80
	v_or_b32_e32 v233, 0x80, v193
	v_sub_u32_e32 v234, 0xffffffb0, v193
	v_add_u32_e32 v235, 0x6110, v0
	s_movk_i32 s92, 0x1c00
	v_add_u32_e32 v236, v210, v1
	v_mov_b32_e32 v237, 0x358637bd
	v_lshlrev_b32_e32 v170, 2, v116
	s_movk_i32 s16, 0x102
	s_movk_i32 s17, 0x81
	v_mov_b32_e32 v238, 0x41b17218
	v_mov_b32_e32 v239, 0x182
	v_readlane_b32 s8, v247, 23
	v_readlane_b32 s9, v247, 24
	s_branch .LBB0_292

.LBB0_394:
	s_cmp_eq_u32 s100, 2
	s_cbranch_scc0 .Lstag_attn
	v_readlane_b32 s4, v252, 0
	v_readlane_b32 s5, v252, 1
	v_readlane_b32 s6, v252, 2
	v_readlane_b32 s7, v252, 3
	v_readlane_b32 s10, v252, 4
	v_readlane_b32 s11, v252, 5
	v_readlane_b32 s14, v252, 6
	v_readlane_b32 s15, v252, 7
	v_readlane_b32 s16, v252, 8
	v_readlane_b32 s17, v252, 9
	v_readlane_b32 s18, v252, 10
	v_readlane_b32 s19, v252, 11
	v_readlane_b32 s28, v252, 12
	v_readlane_b32 s29, v252, 13
	v_readlane_b32 s30, v252, 14
	v_readlane_b32 s31, v252, 15
	v_readlane_b32 s34, v252, 16
	v_readlane_b32 s35, v252, 17
	v_readlane_b32 s41, v252, 18
	v_readlane_b32 s43, v252, 19
	v_readlane_b32 s54, v252, 20
	v_readlane_b32 s55, v252, 21
	v_readlane_b32 s56, v252, 22
	v_readlane_b32 s57, v252, 23
	v_readlane_b32 s58, v252, 24
	v_readlane_b32 s88, v252, 25
	v_readlane_b32 s89, v252, 26
	v_readlane_b32 s90, v252, 27
	v_readlane_b32 s91, v252, 28
	v_readlane_b32 s96, v252, 29
	s_branch .Lstag_done

.LBB0_422:
	s_cmp_eq_u32 s100, 1
	s_cbranch_scc0 .Lstag_done
	s_mov_b32 s100, 2
	v_writelane_b32 v252, s4, 0
	v_writelane_b32 v252, s5, 1
	v_writelane_b32 v252, s6, 2
	v_writelane_b32 v252, s7, 3
	v_writelane_b32 v252, s10, 4
	v_writelane_b32 v252, s11, 5
	v_writelane_b32 v252, s14, 6
	v_writelane_b32 v252, s15, 7
	v_writelane_b32 v252, s16, 8
	v_writelane_b32 v252, s17, 9
	v_writelane_b32 v252, s18, 10
	v_writelane_b32 v252, s19, 11
	v_writelane_b32 v252, s28, 12
	v_writelane_b32 v252, s29, 13
	v_writelane_b32 v252, s30, 14
	v_writelane_b32 v252, s31, 15
	v_writelane_b32 v252, s34, 16
	v_writelane_b32 v252, s35, 17
	v_writelane_b32 v252, s41, 18
	v_writelane_b32 v252, s43, 19
	v_writelane_b32 v252, s54, 20
	v_writelane_b32 v252, s55, 21
	v_writelane_b32 v252, s56, 22
	v_writelane_b32 v252, s57, 23
	v_writelane_b32 v252, s58, 24
	v_writelane_b32 v252, s88, 25
	v_writelane_b32 v252, s89, 26
	v_writelane_b32 v252, s90, 27
	v_writelane_b32 v252, s91, 28
	v_writelane_b32 v252, s96, 29
	s_branch .Lstag_sample

	.amdhsa_kernel _Z3fwd4Args
		.amdhsa_group_segment_fixed_size 0
		.amdhsa_private_segment_fixed_size 0
		.amdhsa_kernarg_size 408
		.amdhsa_user_sgpr_count 2
		.amdhsa_user_sgpr_dispatch_ptr 0
		.amdhsa_user_sgpr_queue_ptr 0
		.amdhsa_user_sgpr_kernarg_segment_ptr 1
		.amdhsa_user_sgpr_dispatch_id 0
		.amdhsa_user_sgpr_kernarg_preload_length 0
		.amdhsa_user_sgpr_kernarg_preload_offset 0
		.amdhsa_user_sgpr_private_segment_size 0
		.amdhsa_uses_dynamic_stack 0
		.amdhsa_enable_private_segment 0
		.amdhsa_system_sgpr_workgroup_id_x 1
		.amdhsa_system_sgpr_workgroup_id_y 0
		.amdhsa_system_sgpr_workgroup_id_z 0
		.amdhsa_system_sgpr_workgroup_info 0
		.amdhsa_system_vgpr_workitem_id 2
		.amdhsa_next_free_vgpr 256
		.amdhsa_next_free_sgpr 101
		.amdhsa_accum_offset 256
		.amdhsa_reserve_vcc 1
		.amdhsa_float_round_mode_32 0
		.amdhsa_float_round_mode_16_64 0
		.amdhsa_float_denorm_mode_32 3
		.amdhsa_float_denorm_mode_16_64 3
		.amdhsa_dx10_clamp 1
		.amdhsa_ieee_mode 1
		.amdhsa_fp16_overflow 0
		.amdhsa_tg_split 0
		.amdhsa_exception_fp_ieee_invalid_op 0
		.amdhsa_exception_fp_denorm_src 0
		.amdhsa_exception_fp_ieee_div_zero 0
		.amdhsa_exception_fp_ieee_overflow 0
		.amdhsa_exception_fp_ieee_underflow 0
		.amdhsa_exception_fp_ieee_inexact 0
		.amdhsa_exception_int_div_zero 0
	.end_amdhsa_kernel

amdhsa.kernels:
  - .agpr_count:     0
    .args:
      - .offset:         0
        .size:           152
        .value_kind:     by_value
      - .offset:         152
        .size:           4
        .value_kind:     hidden_block_count_x
      - .offset:         156
        .size:           4
        .value_kind:     hidden_block_count_y
      - .offset:         160
        .size:           4
        .value_kind:     hidden_block_count_z
      - .offset:         164
        .size:           2
        .value_kind:     hidden_group_size_x
      - .offset:         166
        .size:           2
        .value_kind:     hidden_group_size_y
      - .offset:         168
        .size:           2
        .value_kind:     hidden_group_size_z
      - .offset:         170
        .size:           2
        .value_kind:     hidden_remainder_x
      - .offset:         172
        .size:           2
        .value_kind:     hidden_remainder_y
      - .offset:         174
        .size:           2
        .value_kind:     hidden_remainder_z
      - .offset:         192
        .size:           8
        .value_kind:     hidden_global_offset_x
      - .offset:         200
        .size:           8
        .value_kind:     hidden_global_offset_y
      - .offset:         208
        .size:           8
        .value_kind:     hidden_global_offset_z
      - .offset:         216
        .size:           2
        .value_kind:     hidden_grid_dims
      - .offset:         240
        .size:           8
        .value_kind:     hidden_multigrid_sync_arg
      - .offset:         272
        .size:           4
        .value_kind:     hidden_dynamic_lds_size
    .group_segment_fixed_size: 0
    .kernarg_segment_align: 8
    .kernarg_segment_size: 408
    .language:       OpenCL C
    .language_version:
      - 2
      - 0
    .max_flat_workgroup_size: 512
    .name:           _Z3fwd4Args
    .private_segment_fixed_size: 0
    .sgpr_count:     107
    .sgpr_spill_count: 52
    .symbol:         _Z3fwd4Args.kd
    .uniform_work_group_size: 1
    .uses_dynamic_stack: false
    .vgpr_count:     256
    .vgpr_spill_count: 0
    .wavefront_size: 64
